# GEMM 1408-tile phases: last round split into column-half tiles over all 256 CUs (skip bj=1 MFMA groups), swiglu epilogue half path
# baseline (speedup 1.0000x reference)
; template <class Epi, class Sched, bool ALIGN_EPI = false, bool SP2 = false>
; __device__ __forceinline__ void gemm_phase(PG8_LAS unsigned char* lds, const Gemm g, const Sched& S, const Epi& E, int tid_in) {
;     ...
;     Unit cur, nxt; int ui = 0;
;     if (!S.next(0, cur)) return;
;     f32x4 acc[2][2][4][2];
; #pragma unroll
;     for (int a = 0; a < 2; ++a)
; #pragma unroll
;         for (int b = 0; b < 2; ++b)
; #pragma unroll
;             for (int m = 0; m < 4; ++m)
; #pragma unroll
;                 for (int n = 0; n < 2; ++n) acc[a][b][m][n] = (f32x4){0.f, 0.f, 0.f, 0.f};
;     bf16x8 At[4][2], B0[2][2], B1[2][2];
;     const char* cA = (const char*)g.A + (size_t)cur.pm * tstep; const char* cB = (const char*)g.Bt + (size_t)cur.pn * tstep;
;     S.a_ready(cur);
.LBB0_429:
	v_writelane_b32 v255, s23, 62
	v_writelane_b32 v255, s23, 63
	v_mov_b32_e32 v12, v217
	s_andn2_b64 vcc, exec, s[4:5]
	s_cbranch_vccnz .LBB0_431
	v_readlane_b32 s74, v255, 52
	s_waitcnt lgkmcnt(0)
	v_readlane_b32 s72, v255, 54
	v_readlane_b32 s70, v255, 56
	v_readlane_b32 s68, v255, 58
	s_movk_i32 s94, 0x100
	s_mov_b32 s66, 4
	s_mov_b64 s[76:77], 0
	s_movk_i32 s67, 0x400
	s_mov_b32 s78, 0
	v_readlane_b32 s75, v255, 53
	v_readlane_b32 s73, v255, 55
	s_movk_i32 s46, 0x400
	v_readlane_b32 s71, v255, 57
	v_readlane_b32 s69, v255, 59

;     __host__ __device__ bool next(int i, Unit& u) const {
;         const long L = (long)i * G + c; if (L >= nwg) return false;
;         int wgid = (int)L; { const int q = nwg / NXCD, r = nwg % NXCD, xcd = wgid % NXCD, off = wgid / NXCD; wgid = (xcd < r ? xcd * (q + 1) : r * (q + 1) + (xcd - r) * q) + off; }
;         const int nig = WGM * nN, gid = wgid / nig, fm = gid * WGM, gsz = (nM - fm) < WGM ? (nM - fm) : WGM;
;         u.pm = fm + ((wgid % nig) % gsz); u.pn = (wgid % nig) / gsz; return true;
; template <class Epi, class Sched, bool ALIGN_EPI = false, bool SP2 = false>
; __device__ __forceinline__ void gemm_phase(PG8_LAS unsigned char* lds, const Gemm g, const Sched& S, const Epi& E, int tid_in) {
;     ...
;         cur = nxt; cA = nA; cB = nB; ++ui;
.LBB0_438:
	s_andn2_b64 vcc, exec, s[4:5]
	v_readlane_b32 s4, v255, 62
	s_nop 3
	v_writelane_b32 v255, s4, 63
	s_mov_b32 s41, s14
	s_mov_b32 s24, s15
	s_mov_b64 s[28:29], s[84:85]
	s_mov_b64 s[86:87], s[82:83]
	s_cbranch_vccz .LBB0_427
.LBB0_439:
	s_add_i32 s12, s12, 1
	s_mul_i32 s4, s12, s42
	s_mul_hi_u32 s5, s12, s16
	s_add_i32 s5, s5, s4
	s_mul_i32 s4, s12, s16
	s_add_u32 s6, s4, s2
	s_addc_u32 s7, s5, s17
	v_writelane_b32 v255, s23, 62
	s_cmp_eq_u32 s12, 5
	s_cbranch_scc0 .Lht_no
	s_cmpk_eq_u32 s30, 0x580
	s_cbranch_scc0 .Lht_no
	s_cmpk_eq_u32 s16, 0x100
	s_cbranch_scc0 .Lht_no
	s_lshr_b32 s6, s2, 1
	s_add_u32 s6, s4, s6
	s_addc_u32 s7, s5, 0
	s_and_b32 s14, s2, 1
	s_add_i32 s14, s14, 1
	s_nop 0
	v_writelane_b32 v255, s14, 62
.Lht_no:
	v_mov_b64_e32 v[0:1], s[30:31]
	v_cmp_ge_i64_e32 vcc, s[6:7], v[0:1]
	v_cmp_lt_i64_e64 s[4:5], s[6:7], v[0:1]
	s_cbranch_vccnz .LBB0_441
	s_ashr_i32 s7, s6, 31
	s_lshr_b32 s7, s7, 29
	s_add_i32 s7, s6, s7
	s_ashr_i32 s14, s7, 3
	s_and_b32 s7, s7, -8
	s_sub_i32 s6, s6, s7
	s_lshr_b32 s7, s6, 31
	s_or_b32 s7, s19, s7
	s_mul_i32 s6, s7, s6
	s_add_i32 s6, s6, s14
	s_abs_i32 s14, s6
	s_mul_hi_u32 s15, s14, s13
	s_mul_i32 s25, s15, s11
	s_ashr_i32 s7, s6, 31
	s_sub_i32 s14, s14, s25
	s_xor_b32 s7, s7, s10
	s_add_i32 s25, s15, 1
	s_sub_i32 s51, s14, s11
	s_cmp_ge_u32 s14, s11
	s_cselect_b32 s15, s25, s15
	s_cselect_b32 s14, s51, s14
	s_add_i32 s25, s15, 1
	s_cmp_ge_u32 s14, s11
	s_cselect_b32 s14, s25, s15
	s_xor_b32 s14, s14, s7
	s_sub_i32 s7, s14, s7
	s_lshl_b32 s15, s7, 3
	s_sub_i32 s14, 64, s15
	s_min_i32 s25, s14, 8
	s_abs_i32 s14, s25
	v_cvt_f32_u32_e32 v0, s14
	s_sub_i32 s82, 0, s14
	s_mul_i32 s7, s7, s19
	s_sub_i32 s6, s6, s7
	v_rcp_iflag_f32_e32 v0, v0
	s_abs_i32 s51, s6
	s_xor_b32 s7, s6, s25
	s_ashr_i32 s7, s7, 31
	v_mul_f32_e32 v0, 0x4f7ffffe, v0
	v_cvt_u32_f32_e32 v0, v0
	s_nop 0
	v_readfirstlane_b32 s83, v0
	s_mul_i32 s82, s82, s83
	s_mul_hi_u32 s82, s83, s82
	s_add_i32 s83, s83, s82
	s_mul_hi_u32 s82, s51, s83
	s_mul_i32 s83, s82, s14
	s_sub_i32 s51, s51, s83
	s_add_i32 s83, s82, 1
	s_sub_i32 s84, s51, s14
	s_cmp_ge_u32 s51, s14
	s_cselect_b32 s82, s83, s82
	s_cselect_b32 s51, s84, s51
	s_add_i32 s83, s82, 1
	s_cmp_ge_u32 s51, s14
	s_cselect_b32 s14, s83, s82
	s_xor_b32 s14, s14, s7
	s_sub_i32 s14, s14, s7
	s_mul_i32 s7, s14, s25
	s_sub_i32 s6, s6, s7
	s_add_i32 s15, s6, s15

; #define PG8_STAGE(bufoff, gbase, voff) do { _Pragma("unroll") for (int _i = 0; _i < 2; ++_i) \
;         __builtin_amdgcn_global_load_lds((const unsigned*)((const char*)(gbase) + (voff)[_i]), (PG8_LAS unsigned*)(lds + (bufoff) + ldsw + _i * 8192), 16, 0, 0); } while (0)
; #define PG8_LDA(dst, b, h) do { _Pragma("unroll") for (int m = 0; m < 4; ++m) _Pragma("unroll") for (int k = 0; k < 2; ++k) dst[m][k] = *(const PG8_LAS bf16x8*)(lds + PG8_SA(b, h) + aoff + m * 2048 + k * 1024); } while (0)
; #define PG8_LDB(dst, b, h) do { _Pragma("unroll") for (int n = 0; n < 2; ++n) _Pragma("unroll") for (int k = 0; k < 2; ++k) dst[n][k] = *(const PG8_LAS bf16x8*)(lds + PG8_SB(b, h) + boff + n * 2048 + k * 1024); } while (0)
; #define PG8_MMA(ai, bj, At, Bt) do { __builtin_amdgcn_s_setprio(1); _Pragma("unroll") for (int m = 0; m < 4; ++m) _Pragma("unroll") for (int n = 0; n < 2; ++n) _Pragma("unroll") for (int k = 0; k < 2; ++k) \
;         acc[ai][bj][m][n] = __builtin_amdgcn_mfma_f32_16x16x32_bf16(Bt[n][k], At[m][k], acc[ai][bj][m][n], 0, 0, 0); __builtin_amdgcn_s_setprio(0); } while (0)
; #define PG8_WAIT_V(n) asm volatile("s_waitcnt vmcnt(" #n ")" ::: "memory")
; template <class Epi, class Sched, bool ALIGN_EPI = false, bool SP2 = false>
; __device__ __forceinline__ void gemm_phase(PG8_LAS unsigned char* lds, const Gemm g, const Sched& S, const Epi& E, int tid_in) {
;     ...
;         for (int t = 0; t < nt; t += 2) {
;             const bool last = (t == nt - 2);
;             const char* a1 = cA + (size_t)(t + 1) * kstep;
;             const char* a2 = last ? nA : cA + (size_t)(t + 2) * kstep; const char* b2 = last ? nB : cB + (size_t)(t + 2) * kstep;
;             const char* a3 = a2 + kstep; const char* b3 = b2 + kstep;
;             if (last && has_next) S.a_ready(nxt);
;             if constexpr (SP2) {
;             PG8_LDB(B0, 0, 0); PG8_LDB(B1, 0, 1); PG8_SCHED; PG8_LDA(At, 0, 0); PG8_STAGE(PG8_SA(1, 1), a1 + hstep, voffA);
;             PG8_WAIT_V(8); PG8_WAIT_L(0); PG8_BAR; PG8_MMA(0, 0, At, B0); PG8_MMA(0, 1, At, B1); PG8_BAR; PG8_SCHED;
;     ...
; #pragma unroll
;         for (int a = 0; a < 2; ++a)
; #pragma unroll
;             for (int b = 0; b < 2; ++b)
; #pragma unroll
;                 for (int m = 0; m < 4; ++m)
; #pragma unroll
;                     for (int n = 0; n < 2; ++n) acc[a][b][m][n] = (f32x4){0.f, 0.f, 0.f, 0.f};
.LBB0_445:
	v_readlane_b32 s4, v255, 62
	s_nop 0
	s_cmp_eq_u32 s4, 2
	s_cbranch_scc0 .Lht_nob
	s_add_u32 s84, s84, 0x40000
	s_addc_u32 s85, s85, 0
.Lht_nob:
	s_add_u32 s4, s86, 0x80
	s_addc_u32 s5, s87, 0
	s_add_u32 s25, s28, 0x100
	v_mov_b32_e32 v0, 0
	s_addc_u32 s51, s29, 0
	s_mov_b32 s28, 0
	v_mov_b32_e32 v1, v0
	v_mov_b32_e32 v2, v0
	v_mov_b32_e32 v3, v0
	v_mov_b32_e32 v4, v0
	v_mov_b32_e32 v5, v0
	v_mov_b32_e32 v6, v0
	v_mov_b32_e32 v7, v0
	v_mov_b32_e32 v16, v0
	v_mov_b32_e32 v17, v0
	v_mov_b32_e32 v18, v0
	v_mov_b32_e32 v19, v0
	v_mov_b32_e32 v20, v0
	v_mov_b32_e32 v21, v0
	v_mov_b32_e32 v22, v0
	v_mov_b32_e32 v23, v0
	v_mov_b32_e32 v32, v0
	v_mov_b32_e32 v33, v0
	v_mov_b32_e32 v34, v0
	v_mov_b32_e32 v35, v0
	v_mov_b32_e32 v36, v0
	v_mov_b32_e32 v37, v0
	v_mov_b32_e32 v38, v0
	v_mov_b32_e32 v39, v0
	v_mov_b32_e32 v48, v0
	v_mov_b32_e32 v49, v0
	v_mov_b32_e32 v50, v0
	v_mov_b32_e32 v51, v0
	v_mov_b32_e32 v52, v0
	v_mov_b32_e32 v53, v0
	v_mov_b32_e32 v54, v0
	v_mov_b32_e32 v55, v0
	v_mov_b32_e32 v8, v0
	v_mov_b32_e32 v9, v0
	v_mov_b32_e32 v10, v0
	v_mov_b32_e32 v11, v0
	v_mov_b32_e32 v12, v0
	v_mov_b32_e32 v13, v0
	v_mov_b32_e32 v14, v0
	v_mov_b32_e32 v15, v0
	v_mov_b32_e32 v24, v0
	v_mov_b32_e32 v25, v0
	v_mov_b32_e32 v26, v0
	v_mov_b32_e32 v27, v0
	v_mov_b32_e32 v28, v0
	v_mov_b32_e32 v29, v0
	v_mov_b32_e32 v30, v0
	v_mov_b32_e32 v31, v0
	v_mov_b32_e32 v40, v0
	v_mov_b32_e32 v41, v0
	v_mov_b32_e32 v42, v0
	v_mov_b32_e32 v43, v0
	v_mov_b32_e32 v44, v0
	v_mov_b32_e32 v45, v0
	v_mov_b32_e32 v46, v0
	v_mov_b32_e32 v47, v0
	v_mov_b32_e32 v56, v0
	v_mov_b32_e32 v57, v0
	v_mov_b32_e32 v58, v0
	v_mov_b32_e32 v59, v0
	v_mov_b32_e32 v60, v0
	v_mov_b32_e32 v61, v0
	v_mov_b32_e32 v62, v0
	v_mov_b32_e32 v63, v0
	v_mov_b32_e32 v64, v0
	v_mov_b32_e32 v65, v0
	v_mov_b32_e32 v66, v0
	v_mov_b32_e32 v67, v0
	v_mov_b32_e32 v68, v0
	v_mov_b32_e32 v69, v0
	v_mov_b32_e32 v70, v0
	v_mov_b32_e32 v71, v0
	v_mov_b32_e32 v80, v0
	v_mov_b32_e32 v81, v0
	s_waitcnt vmcnt(0)
	v_mov_b32_e32 v82, v0
	v_mov_b32_e32 v83, v0
	v_mov_b32_e32 v84, v0
	v_mov_b32_e32 v85, v0
	v_mov_b32_e32 v86, v0
	v_mov_b32_e32 v87, v0
	v_mov_b32_e32 v96, v0
	v_mov_b32_e32 v97, v0
	v_mov_b32_e32 v98, v0
	v_mov_b32_e32 v99, v0
	v_mov_b32_e32 v100, v0
	v_mov_b32_e32 v101, v0
	v_mov_b32_e32 v102, v0
	v_mov_b32_e32 v103, v0
	v_mov_b32_e32 v112, v0
	v_mov_b32_e32 v113, v0
	v_mov_b32_e32 v114, v0
	v_mov_b32_e32 v115, v0
	v_mov_b32_e32 v116, v0
	v_mov_b32_e32 v117, v0
	v_mov_b32_e32 v118, v0
	v_mov_b32_e32 v119, v0
	v_mov_b32_e32 v72, v0
	v_mov_b32_e32 v73, v0
	v_mov_b32_e32 v74, v0
	v_mov_b32_e32 v75, v0
	v_mov_b32_e32 v76, v0
	v_mov_b32_e32 v77, v0
	v_mov_b32_e32 v78, v0
	v_mov_b32_e32 v79, v0
	v_mov_b32_e32 v88, v0
	v_mov_b32_e32 v89, v0
	v_mov_b32_e32 v90, v0
	v_mov_b32_e32 v91, v0
	v_mov_b32_e32 v92, v0
	v_mov_b32_e32 v93, v0
	v_mov_b32_e32 v94, v0
	v_mov_b32_e32 v95, v0
	v_mov_b32_e32 v104, v0
	v_mov_b32_e32 v105, v0
	v_mov_b32_e32 v106, v0
	v_mov_b32_e32 v107, v0
	v_mov_b32_e32 v108, v0
	v_mov_b32_e32 v109, v0
	v_mov_b32_e32 v110, v0
	v_mov_b32_e32 v111, v0
	v_mov_b32_e32 v120, v0
	v_mov_b32_e32 v121, v0
	v_mov_b32_e32 v122, v0
	v_mov_b32_e32 v123, v0
	v_mov_b32_e32 v124, v0
	v_mov_b32_e32 v125, v0
	v_mov_b32_e32 v126, v0
	v_mov_b32_e32 v127, v0
	v_readlane_b32 vcc_lo, v255, 63
.LBB0_446:
	s_add_i32 s86, s28, 2
	s_add_u32 s87, s4, 0x80
	s_addc_u32 s29, s5, 0
	s_add_i32 s90, 0, 0x10000
	s_cmp_eq_u32 s46, s28
	s_cselect_b32 s29, s83, s29
	s_cselect_b32 s28, s82, s87
	v_add_u32_e32 v152, s90, v147
	s_cselect_b32 s89, s85, s51
	s_cselect_b32 s88, s84, s25
	s_add_i32 s87, 0, 0x14000
	ds_read_b128 v[138:141], v152
	ds_read_b128 v[142:145], v152 offset:1024
	ds_read_b128 v[160:163], v152 offset:2048
	ds_read_b128 v[164:167], v152 offset:3072
	v_add_u32_e32 v152, s87, v147
	ds_read_b128 v[168:171], v152
	ds_read_b128 v[176:179], v152 offset:1024
	ds_read_b128 v[180:183], v152 offset:2048
	ds_read_b128 v[184:187], v152 offset:3072
	v_lshl_add_u64 v[172:173], s[4:5], 0, v[134:135]
	s_add_i32 m0, s96, 0xc000
	ds_read_b128 v[188:191], v158
	ds_read_b128 v[192:195], v158 offset:1024
	ds_read_b128 v[220:223], v158 offset:2048
	ds_read_b128 v[224:227], v158 offset:3072
	ds_read_b128 v[228:231], v158 offset:4096
	ds_read_b128 v[232:235], v158 offset:5120
	ds_read_b128 v[236:239], v158 offset:6144
	ds_read_b128 v[240:243], v158 offset:7168
	global_load_lds_dwordx4 v[172:173], off
	v_lshl_add_u64 v[172:173], s[4:5], 0, v[136:137]
	s_add_i32 m0, s96, 0xe000
	s_nop 0
	global_load_lds_dwordx4 v[172:173], off
	s_waitcnt vmcnt(8)
	s_waitcnt lgkmcnt(0)
	s_barrier
	s_setprio 1
	s_waitcnt lgkmcnt(0)
	v_mfma_f32_16x16x32_bf16 v[124:127], v[138:141], v[188:191], v[124:127]
	v_mfma_f32_16x16x32_bf16 v[120:123], v[160:163], v[188:191], v[120:123]
	v_mfma_f32_16x16x32_bf16 v[108:111], v[138:141], v[220:223], v[108:111]
	v_mfma_f32_16x16x32_bf16 v[104:107], v[160:163], v[220:223], v[104:107]
	v_mfma_f32_16x16x32_bf16 v[92:95], v[138:141], v[228:231], v[92:95]
	v_mfma_f32_16x16x32_bf16 v[88:91], v[160:163], v[228:231], v[88:91]
	v_mfma_f32_16x16x32_bf16 v[76:79], v[138:141], v[236:239], v[76:79]
	v_mfma_f32_16x16x32_bf16 v[72:75], v[160:163], v[236:239], v[72:75]
	v_mfma_f32_16x16x32_bf16 v[124:127], v[142:145], v[192:195], v[124:127]
	v_mfma_f32_16x16x32_bf16 v[120:123], v[164:167], v[192:195], v[120:123]
	v_mfma_f32_16x16x32_bf16 v[108:111], v[142:145], v[224:227], v[108:111]
	v_mfma_f32_16x16x32_bf16 v[104:107], v[164:167], v[224:227], v[104:107]
	v_mfma_f32_16x16x32_bf16 v[92:95], v[142:145], v[232:235], v[92:95]
	v_mfma_f32_16x16x32_bf16 v[88:91], v[164:167], v[232:235], v[88:91]
	v_mfma_f32_16x16x32_bf16 v[76:79], v[142:145], v[240:243], v[76:79]
	v_mfma_f32_16x16x32_bf16 v[72:75], v[164:167], v[240:243], v[72:75]
	s_setprio 0
	s_cmp_lg_u32 vcc_lo, 0
	s_cbranch_scc1 .Lht_skip0
	s_setprio 1
	v_mfma_f32_16x16x32_bf16 v[116:119], v[168:171], v[188:191], v[116:119]
	v_mfma_f32_16x16x32_bf16 v[112:115], v[180:183], v[188:191], v[112:115]
	v_mfma_f32_16x16x32_bf16 v[100:103], v[168:171], v[220:223], v[100:103]
	v_mfma_f32_16x16x32_bf16 v[96:99], v[180:183], v[220:223], v[96:99]
	v_mfma_f32_16x16x32_bf16 v[84:87], v[168:171], v[228:231], v[84:87]
	v_mfma_f32_16x16x32_bf16 v[80:83], v[180:183], v[228:231], v[80:83]
	v_mfma_f32_16x16x32_bf16 v[68:71], v[168:171], v[236:239], v[68:71]
	v_mfma_f32_16x16x32_bf16 v[64:67], v[180:183], v[236:239], v[64:67]
	v_mfma_f32_16x16x32_bf16 v[116:119], v[176:179], v[192:195], v[116:119]
	v_mfma_f32_16x16x32_bf16 v[112:115], v[184:187], v[192:195], v[112:115]
	v_mfma_f32_16x16x32_bf16 v[100:103], v[176:179], v[224:227], v[100:103]
	v_mfma_f32_16x16x32_bf16 v[96:99], v[184:187], v[224:227], v[96:99]
	v_mfma_f32_16x16x32_bf16 v[84:87], v[176:179], v[232:235], v[84:87]
	v_mfma_f32_16x16x32_bf16 v[80:83], v[184:187], v[232:235], v[80:83]
	v_mfma_f32_16x16x32_bf16 v[68:71], v[176:179], v[240:243], v[68:71]
	v_mfma_f32_16x16x32_bf16 v[64:67], v[184:187], v[240:243], v[64:67]
; #define PG8_STAGE(bufoff, gbase, voff) do { _Pragma("unroll") for (int _i = 0; _i < 2; ++_i) \
;         __builtin_amdgcn_global_load_lds((const unsigned*)((const char*)(gbase) + (voff)[_i]), (PG8_LAS unsigned*)(lds + (bufoff) + ldsw + _i * 8192), 16, 0, 0); } while (0)
; #define PG8_LDA(dst, b, h) do { _Pragma("unroll") for (int m = 0; m < 4; ++m) _Pragma("unroll") for (int k = 0; k < 2; ++k) dst[m][k] = *(const PG8_LAS bf16x8*)(lds + PG8_SA(b, h) + aoff + m * 2048 + k * 1024); } while (0)
; #define PG8_LDB(dst, b, h) do { _Pragma("unroll") for (int n = 0; n < 2; ++n) _Pragma("unroll") for (int k = 0; k < 2; ++k) dst[n][k] = *(const PG8_LAS bf16x8*)(lds + PG8_SB(b, h) + boff + n * 2048 + k * 1024); } while (0)
; #define PG8_MMA(ai, bj, At, Bt) do { __builtin_amdgcn_s_setprio(1); _Pragma("unroll") for (int m = 0; m < 4; ++m) _Pragma("unroll") for (int n = 0; n < 2; ++n) _Pragma("unroll") for (int k = 0; k < 2; ++k) \
;         acc[ai][bj][m][n] = __builtin_amdgcn_mfma_f32_16x16x32_bf16(Bt[n][k], At[m][k], acc[ai][bj][m][n], 0, 0, 0); __builtin_amdgcn_s_setprio(0); } while (0)
; #define PG8_WAIT_V(n) asm volatile("s_waitcnt vmcnt(" #n ")" ::: "memory")
; #define PG8_WAIT_L(n) asm volatile("s_waitcnt lgkmcnt(" #n ")" ::: "memory")
; #define PG8_BAR __builtin_amdgcn_s_barrier()
; #define PG8_SCHED __builtin_amdgcn_sched_barrier(0)
; template <class Epi, class Sched, bool ALIGN_EPI = false, bool SP2 = false>
; __device__ __forceinline__ void gemm_phase(PG8_LAS unsigned char* lds, const Gemm g, const Sched& S, const Epi& E, int tid_in) {
;     ...
;             PG8_LDB(B0, 0, 0); PG8_LDB(B1, 0, 1); PG8_SCHED; PG8_LDA(At, 0, 0); PG8_STAGE(PG8_SA(1, 1), a1 + hstep, voffA);
;             PG8_WAIT_V(8); PG8_WAIT_L(0); PG8_BAR; PG8_MMA(0, 0, At, B0); PG8_MMA(0, 1, At, B1); PG8_BAR; PG8_SCHED;
;             PG8_LDA(At, 0, 1); PG8_STAGE(PG8_SB(0, 0), b2, voffB); PG8_STAGE(PG8_SB(0, 1), b2 + hstep, voffB); PG8_STAGE(PG8_SA(0, 0), a2, voffA);
;             PG8_WAIT_V(8); PG8_WAIT_L(0); PG8_BAR; PG8_MMA(1, 0, At, B0); PG8_MMA(1, 1, At, B1); PG8_BAR; PG8_SCHED;
;             PG8_LDB(B0, 1, 0); PG8_LDB(B1, 1, 1); PG8_SCHED; PG8_LDA(At, 1, 0); PG8_STAGE(PG8_SA(0, 1), a2 + hstep, voffA);
;             PG8_WAIT_V(8); PG8_WAIT_L(0); PG8_BAR; PG8_MMA(0, 0, At, B0); PG8_MMA(0, 1, At, B1); PG8_BAR; PG8_SCHED;
.Lht_skip0:
	s_setprio 0
	s_barrier
	s_add_i32 s90, s90, s95
	v_lshl_add_u64 v[172:173], s[88:89], 0, v[128:129]
	s_mov_b32 m0, s90
	ds_read_b128 v[188:191], v158 offset:16384
	ds_read_b128 v[192:195], v158 offset:17408
	ds_read_b128 v[220:223], v158 offset:18432
	ds_read_b128 v[224:227], v158 offset:19456
	ds_read_b128 v[228:231], v158 offset:20480
	ds_read_b128 v[232:235], v158 offset:21504
	ds_read_b128 v[236:239], v158 offset:22528
	ds_read_b128 v[240:243], v158 offset:23552
	global_load_lds_dwordx4 v[172:173], off
	s_add_i32 m0, s90, 0x2000
	v_lshl_add_u64 v[196:197], s[88:89], 0, v[130:131]
	s_add_u32 s88, s88, s22
	s_addc_u32 s89, s89, 0
	s_add_i32 s87, s87, s95
	global_load_lds_dwordx4 v[196:197], off
	v_lshl_add_u64 v[244:245], s[88:89], 0, v[128:129]
	s_mov_b32 m0, s87
	v_lshl_add_u64 v[246:247], s[88:89], 0, v[130:131]
	global_load_lds_dwordx4 v[244:245], off
	s_add_i32 m0, s87, 0x2000
	v_lshl_add_u64 v[248:249], s[28:29], 0, v[128:129]
	global_load_lds_dwordx4 v[246:247], off
	s_mov_b32 m0, s96
	v_lshl_add_u64 v[250:251], s[28:29], 0, v[130:131]
	global_load_lds_dwordx4 v[248:249], off
	s_mov_b32 m0, s97
	s_nop 0
	global_load_lds_dwordx4 v[250:251], off
	s_waitcnt vmcnt(8)
	s_waitcnt lgkmcnt(0)
	s_barrier
	s_setprio 1
	s_waitcnt lgkmcnt(0)
	v_mfma_f32_16x16x32_bf16 v[60:63], v[138:141], v[188:191], v[60:63]
	v_mfma_f32_16x16x32_bf16 v[56:59], v[160:163], v[188:191], v[56:59]
	v_mfma_f32_16x16x32_bf16 v[44:47], v[138:141], v[220:223], v[44:47]
	v_mfma_f32_16x16x32_bf16 v[40:43], v[160:163], v[220:223], v[40:43]
	v_mfma_f32_16x16x32_bf16 v[28:31], v[138:141], v[228:231], v[28:31]
	v_mfma_f32_16x16x32_bf16 v[24:27], v[160:163], v[228:231], v[24:27]
	v_mfma_f32_16x16x32_bf16 v[12:15], v[138:141], v[236:239], v[12:15]
	v_mfma_f32_16x16x32_bf16 v[8:11], v[160:163], v[236:239], v[8:11]
	v_mfma_f32_16x16x32_bf16 v[60:63], v[142:145], v[192:195], v[60:63]
	v_mfma_f32_16x16x32_bf16 v[56:59], v[164:167], v[192:195], v[56:59]
	v_mfma_f32_16x16x32_bf16 v[44:47], v[142:145], v[224:227], v[44:47]
	v_mfma_f32_16x16x32_bf16 v[40:43], v[164:167], v[224:227], v[40:43]
	v_mfma_f32_16x16x32_bf16 v[28:31], v[142:145], v[232:235], v[28:31]
	v_mfma_f32_16x16x32_bf16 v[24:27], v[164:167], v[232:235], v[24:27]
	v_mfma_f32_16x16x32_bf16 v[12:15], v[142:145], v[240:243], v[12:15]
	v_mfma_f32_16x16x32_bf16 v[8:11], v[164:167], v[240:243], v[8:11]
	s_setprio 0
	s_cmp_lg_u32 vcc_lo, 0
	s_cbranch_scc1 .Lht_skip1
	s_setprio 1
	v_mfma_f32_16x16x32_bf16 v[52:55], v[168:171], v[188:191], v[52:55]
	v_mfma_f32_16x16x32_bf16 v[48:51], v[180:183], v[188:191], v[48:51]
	v_mfma_f32_16x16x32_bf16 v[36:39], v[168:171], v[220:223], v[36:39]
	v_mfma_f32_16x16x32_bf16 v[32:35], v[180:183], v[220:223], v[32:35]
	v_mfma_f32_16x16x32_bf16 v[20:23], v[168:171], v[228:231], v[20:23]
	v_mfma_f32_16x16x32_bf16 v[16:19], v[180:183], v[228:231], v[16:19]
	v_mfma_f32_16x16x32_bf16 v[4:7], v[168:171], v[236:239], v[4:7]
	v_mfma_f32_16x16x32_bf16 v[0:3], v[180:183], v[236:239], v[0:3]
	v_mfma_f32_16x16x32_bf16 v[52:55], v[176:179], v[192:195], v[52:55]
	v_mfma_f32_16x16x32_bf16 v[48:51], v[184:187], v[192:195], v[48:51]
	v_mfma_f32_16x16x32_bf16 v[36:39], v[176:179], v[224:227], v[36:39]
	v_mfma_f32_16x16x32_bf16 v[32:35], v[184:187], v[224:227], v[32:35]
	v_mfma_f32_16x16x32_bf16 v[20:23], v[176:179], v[232:235], v[20:23]
	v_mfma_f32_16x16x32_bf16 v[16:19], v[184:187], v[232:235], v[16:19]
	v_mfma_f32_16x16x32_bf16 v[4:7], v[176:179], v[240:243], v[4:7]
	v_mfma_f32_16x16x32_bf16 v[0:3], v[184:187], v[240:243], v[0:3]
.Lht_skip1:
	s_setprio 0
	s_barrier
	s_add_i32 s87, 0, 0x18000
	v_add_u32_e32 v152, s87, v147
	s_add_i32 s88, 0, 0x1c000
	ds_read_b128 v[138:141], v152
	ds_read_b128 v[142:145], v152 offset:1024
	ds_read_b128 v[160:163], v152 offset:2048
	ds_read_b128 v[164:167], v152 offset:3072
	v_add_u32_e32 v152, s88, v147
	ds_read_b128 v[168:171], v152
	ds_read_b128 v[176:179], v152 offset:1024
	ds_read_b128 v[180:183], v152 offset:2048
	ds_read_b128 v[184:187], v152 offset:3072
	s_add_u32 s28, s28, s22
	s_addc_u32 s29, s29, 0
	s_mov_b32 m0, s20
	v_lshl_add_u64 v[252:253], s[28:29], 0, v[128:129]
	ds_read_b128 v[188:191], v158 offset:32768
	ds_read_b128 v[192:195], v158 offset:33792
	ds_read_b128 v[220:223], v158 offset:34816
	ds_read_b128 v[224:227], v158 offset:35840
	ds_read_b128 v[228:231], v158 offset:36864
	ds_read_b128 v[232:235], v158 offset:37888
	ds_read_b128 v[236:239], v158 offset:38912
	ds_read_b128 v[240:243], v158 offset:39936
	global_load_lds_dwordx4 v[252:253], off
	v_lshl_add_u64 v[252:253], s[28:29], 0, v[130:131]
	s_mov_b32 m0, s21
	s_nop 0
	global_load_lds_dwordx4 v[252:253], off
	s_waitcnt vmcnt(8)
	s_waitcnt lgkmcnt(0)
	s_barrier
	s_setprio 1
	s_waitcnt lgkmcnt(0)
	v_mfma_f32_16x16x32_bf16 v[124:127], v[138:141], v[188:191], v[124:127]
	v_mfma_f32_16x16x32_bf16 v[120:123], v[160:163], v[188:191], v[120:123]
	v_mfma_f32_16x16x32_bf16 v[108:111], v[138:141], v[220:223], v[108:111]
	v_mfma_f32_16x16x32_bf16 v[104:107], v[160:163], v[220:223], v[104:107]
	v_mfma_f32_16x16x32_bf16 v[92:95], v[138:141], v[228:231], v[92:95]
	v_mfma_f32_16x16x32_bf16 v[88:91], v[160:163], v[228:231], v[88:91]
	v_mfma_f32_16x16x32_bf16 v[76:79], v[138:141], v[236:239], v[76:79]
	v_mfma_f32_16x16x32_bf16 v[72:75], v[160:163], v[236:239], v[72:75]
	v_mfma_f32_16x16x32_bf16 v[124:127], v[142:145], v[192:195], v[124:127]
	v_mfma_f32_16x16x32_bf16 v[120:123], v[164:167], v[192:195], v[120:123]
	v_mfma_f32_16x16x32_bf16 v[108:111], v[142:145], v[224:227], v[108:111]
	v_mfma_f32_16x16x32_bf16 v[104:107], v[164:167], v[224:227], v[104:107]
	v_mfma_f32_16x16x32_bf16 v[92:95], v[142:145], v[232:235], v[92:95]
	v_mfma_f32_16x16x32_bf16 v[88:91], v[164:167], v[232:235], v[88:91]
	v_mfma_f32_16x16x32_bf16 v[76:79], v[142:145], v[240:243], v[76:79]
	v_mfma_f32_16x16x32_bf16 v[72:75], v[164:167], v[240:243], v[72:75]
	s_setprio 0
	s_cmp_lg_u32 vcc_lo, 0
	s_cbranch_scc1 .Lht_skip2
; __device__ __forceinline__ unsigned pk_bf16_rne(float lo, float hi) { f32x2 v = {lo, hi}; bf16x2e b = __builtin_convertvector(v, bf16x2e); return __builtin_bit_cast(unsigned, b); }
; __device__ __forceinline__ float silu_f(float x) { return x * __builtin_amdgcn_rcpf(1.0f + __expf(-x)); }
; #define PG8_STAGE(bufoff, gbase, voff) do { _Pragma("unroll") for (int _i = 0; _i < 2; ++_i) \
;         __builtin_amdgcn_global_load_lds((const unsigned*)((const char*)(gbase) + (voff)[_i]), (PG8_LAS unsigned*)(lds + (bufoff) + ldsw + _i * 8192), 16, 0, 0); } while (0)
; #define PG8_LDA(dst, b, h) do { _Pragma("unroll") for (int m = 0; m < 4; ++m) _Pragma("unroll") for (int k = 0; k < 2; ++k) dst[m][k] = *(const PG8_LAS bf16x8*)(lds + PG8_SA(b, h) + aoff + m * 2048 + k * 1024); } while (0)
; #define PG8_WAIT_V(n) asm volatile("s_waitcnt vmcnt(" #n ")" ::: "memory")
; #define PG8_WAIT_L(n) asm volatile("s_waitcnt lgkmcnt(" #n ")" ::: "memory")
;     __device__ __forceinline__ void operator()(const f32x4 (&acc)[2][2][4][2], const Unit& u, int wr, int wc, int fr, int fq) const {
; #pragma unroll
;         for (int ai = 0; ai < 2; ++ai)
; #pragma unroll
;             for (int m = 0; m < 4; ++m) {
;                 const int r = u.pm * BM + ai * HALF + wr * 64 + m * 16 + fr;
; #pragma unroll
;                 for (int bj = 0; bj < 2; ++bj) {
;                     const int cb = u.pn * BM + bj * HALF + wc * 32;
;                     const f32x4 v0 = acc[ai][bj][m][0], v1 = acc[ai][bj][m][1];
;                     if (MODE == 0) {
;                         u32x2e w; w.x = pk_bf16_rne(silu_f(v0[0]) * v1[0], silu_f(v0[1]) * v1[1]); w.y = pk_bf16_rne(silu_f(v0[2]) * v1[2], silu_f(v0[3]) * v1[3]);
;                         *(u32x2e*)(Hh + (size_t)r * ldo + (cb >> 1) + 4 * fq) = w;
; template <class Epi, class Sched, bool ALIGN_EPI = false, bool SP2 = false>
; __device__ __forceinline__ void gemm_phase(PG8_LAS unsigned char* lds, const Gemm g, const Sched& S, const Epi& E, int tid_in) {
;     ...
;             PG8_WAIT_V(8); PG8_WAIT_L(0); PG8_BAR; PG8_MMA(0, 0, At, B0); PG8_MMA(0, 1, At, B1); PG8_BAR; PG8_SCHED;
;             PG8_LDA(At, 1, 1); PG8_STAGE(PG8_SB(1, 0), b3, voffB); PG8_STAGE(PG8_SB(1, 1), b3 + hstep, voffB); PG8_STAGE(PG8_SA(1, 0), a3, voffA);
;             PG8_WAIT_V(8); PG8_WAIT_L(0); PG8_BAR; PG8_MMA(1, 0, At, B0); PG8_MMA(1, 1, At, B1); PG8_BAR; PG8_SCHED;
	s_setprio 1
	v_mfma_f32_16x16x32_bf16 v[116:119], v[168:171], v[188:191], v[116:119]
	v_mfma_f32_16x16x32_bf16 v[112:115], v[180:183], v[188:191], v[112:115]
	v_mfma_f32_16x16x32_bf16 v[100:103], v[168:171], v[220:223], v[100:103]
	v_mfma_f32_16x16x32_bf16 v[96:99], v[180:183], v[220:223], v[96:99]
	v_mfma_f32_16x16x32_bf16 v[84:87], v[168:171], v[228:231], v[84:87]
	v_mfma_f32_16x16x32_bf16 v[80:83], v[180:183], v[228:231], v[80:83]
	v_mfma_f32_16x16x32_bf16 v[68:71], v[168:171], v[236:239], v[68:71]
	v_mfma_f32_16x16x32_bf16 v[64:67], v[180:183], v[236:239], v[64:67]
	v_mfma_f32_16x16x32_bf16 v[116:119], v[176:179], v[192:195], v[116:119]
	v_mfma_f32_16x16x32_bf16 v[112:115], v[184:187], v[192:195], v[112:115]
	v_mfma_f32_16x16x32_bf16 v[100:103], v[176:179], v[224:227], v[100:103]
	v_mfma_f32_16x16x32_bf16 v[96:99], v[184:187], v[224:227], v[96:99]
	v_mfma_f32_16x16x32_bf16 v[84:87], v[176:179], v[232:235], v[84:87]
	v_mfma_f32_16x16x32_bf16 v[80:83], v[184:187], v[232:235], v[80:83]
	v_mfma_f32_16x16x32_bf16 v[68:71], v[176:179], v[240:243], v[68:71]
	v_mfma_f32_16x16x32_bf16 v[64:67], v[184:187], v[240:243], v[64:67]
.Lht_skip2:
	s_setprio 0
	s_barrier
	s_add_i32 s28, s87, s95
	v_lshl_add_u64 v[172:173], v[172:173], 0, s[60:61]
	s_mov_b32 m0, s28
	ds_read_b128 v[188:191], v158 offset:49152
	ds_read_b128 v[192:195], v158 offset:50176
	ds_read_b128 v[220:223], v158 offset:51200
	ds_read_b128 v[224:227], v158 offset:52224
	ds_read_b128 v[228:231], v158 offset:53248
	ds_read_b128 v[232:235], v158 offset:54272
	ds_read_b128 v[236:239], v158 offset:55296
	ds_read_b128 v[240:243], v158 offset:56320
	global_load_lds_dwordx4 v[172:173], off
	v_lshl_add_u64 v[172:173], v[196:197], 0, s[60:61]
	s_add_i32 m0, s28, 0x2000
	s_add_i32 s28, s88, s95
	global_load_lds_dwordx4 v[172:173], off
	v_lshl_add_u64 v[172:173], v[244:245], 0, s[60:61]
	s_mov_b32 m0, s28
	s_nop 0
	global_load_lds_dwordx4 v[172:173], off
	v_lshl_add_u64 v[172:173], v[246:247], 0, s[60:61]
	s_add_i32 m0, s28, 0x2000
	s_nop 0
	global_load_lds_dwordx4 v[172:173], off
	v_lshl_add_u64 v[172:173], v[248:249], 0, s[60:61]
	s_mov_b32 m0, s50
	s_nop 0
	global_load_lds_dwordx4 v[172:173], off
	v_lshl_add_u64 v[172:173], v[250:251], 0, s[60:61]
	s_mov_b32 m0, s18
	s_nop 0
	global_load_lds_dwordx4 v[172:173], off
	s_waitcnt vmcnt(8)
	s_waitcnt lgkmcnt(0)
	s_barrier
	s_setprio 1
	s_waitcnt lgkmcnt(0)
	v_mfma_f32_16x16x32_bf16 v[60:63], v[138:141], v[188:191], v[60:63]
	v_mfma_f32_16x16x32_bf16 v[56:59], v[160:163], v[188:191], v[56:59]
	v_mfma_f32_16x16x32_bf16 v[44:47], v[138:141], v[220:223], v[44:47]
	v_mfma_f32_16x16x32_bf16 v[40:43], v[160:163], v[220:223], v[40:43]
	v_mfma_f32_16x16x32_bf16 v[28:31], v[138:141], v[228:231], v[28:31]
	v_mfma_f32_16x16x32_bf16 v[24:27], v[160:163], v[228:231], v[24:27]
	v_mfma_f32_16x16x32_bf16 v[12:15], v[138:141], v[236:239], v[12:15]
	v_mfma_f32_16x16x32_bf16 v[8:11], v[160:163], v[236:239], v[8:11]
	v_mfma_f32_16x16x32_bf16 v[60:63], v[142:145], v[192:195], v[60:63]
	v_mfma_f32_16x16x32_bf16 v[56:59], v[164:167], v[192:195], v[56:59]
	v_mfma_f32_16x16x32_bf16 v[44:47], v[142:145], v[224:227], v[44:47]
	v_mfma_f32_16x16x32_bf16 v[40:43], v[164:167], v[224:227], v[40:43]
	v_mfma_f32_16x16x32_bf16 v[28:31], v[142:145], v[232:235], v[28:31]
	v_mfma_f32_16x16x32_bf16 v[24:27], v[164:167], v[232:235], v[24:27]
	v_mfma_f32_16x16x32_bf16 v[12:15], v[142:145], v[240:243], v[12:15]
	v_mfma_f32_16x16x32_bf16 v[8:11], v[164:167], v[240:243], v[8:11]
	s_setprio 0
	s_cmp_lg_u32 vcc_lo, 0
	s_cbranch_scc1 .Lht_skip3
	s_setprio 1
	v_mfma_f32_16x16x32_bf16 v[52:55], v[168:171], v[188:191], v[52:55]
	v_mfma_f32_16x16x32_bf16 v[48:51], v[180:183], v[188:191], v[48:51]
	v_mfma_f32_16x16x32_bf16 v[36:39], v[168:171], v[220:223], v[36:39]
	v_mfma_f32_16x16x32_bf16 v[32:35], v[180:183], v[220:223], v[32:35]
	v_mfma_f32_16x16x32_bf16 v[20:23], v[168:171], v[228:231], v[20:23]
	v_mfma_f32_16x16x32_bf16 v[16:19], v[180:183], v[228:231], v[16:19]
	v_mfma_f32_16x16x32_bf16 v[4:7], v[168:171], v[236:239], v[4:7]
	v_mfma_f32_16x16x32_bf16 v[0:3], v[180:183], v[236:239], v[0:3]
	v_mfma_f32_16x16x32_bf16 v[52:55], v[176:179], v[192:195], v[52:55]
	v_mfma_f32_16x16x32_bf16 v[48:51], v[184:187], v[192:195], v[48:51]
	v_mfma_f32_16x16x32_bf16 v[36:39], v[176:179], v[224:227], v[36:39]
	v_mfma_f32_16x16x32_bf16 v[32:35], v[184:187], v[224:227], v[32:35]
	v_mfma_f32_16x16x32_bf16 v[20:23], v[176:179], v[232:235], v[20:23]
	v_mfma_f32_16x16x32_bf16 v[16:19], v[184:187], v[232:235], v[16:19]
	v_mfma_f32_16x16x32_bf16 v[4:7], v[176:179], v[240:243], v[4:7]
	v_mfma_f32_16x16x32_bf16 v[0:3], v[184:187], v[240:243], v[0:3]
.Lht_skip3:
	s_setprio 0
	s_barrier
	s_add_u32 s4, s4, 0x100
	s_addc_u32 s5, s5, 0
	s_add_u32 s25, s25, 0x100
	s_addc_u32 s51, s51, 0
	s_cmp_ge_u32 s86, s33
	s_mov_b32 s28, s86
	s_cbranch_scc0 .LBB0_446
	s_and_b64 vcc, exec, s[62:63]
	s_cbranch_vccz .LBB0_449
	s_barrier
.LBB0_449:
	s_lshl_b32 s25, s24, 8
	s_add_i32 s25, s25, s45
	s_ashr_i32 s4, s25, 12
	v_or_b32_e32 v138, s25, v146
	s_mul_i32 s88, s4, 0x2400
	s_lshl_b32 s4, s41, 8
	v_ashrrev_i32_e32 v139, 31, v138
	s_ashr_i32 s89, s88, 31
	s_or_b32 s86, s4, s37
	v_lshlrev_b64 v[144:145], 10, v[138:139]
	v_lshlrev_b64 v[142:143], 11, v[138:139]
	v_lshlrev_b64 v[140:141], 12, v[138:139]
	s_cmp_eq_u32 s66, 0
	s_cbranch_scc0 .Lepi0_skip
	v_mul_lo_u32 v160, v138, s67
	v_mov_b32_e32 v161, 0
	v_lshl_add_u32 v162, v132, 1, s86
	v_mov_b32_e32 v163, 0
	v_lshl_add_u64 v[160:161], v[160:161], 1, s[74:75]
	s_mov_b32 s4, 0x16000
	s_mov_b32 s5, 0
	s_mov_b32 s28, 0x6e000
	s_mov_b32 s29, 0
	v_lshl_add_u64 v[160:161], v[160:161], 0, v[162:163]
	v_readlane_b32 s90, v255, 63
	s_nop 0
	s_cmp_eq_u32 s90, 0
	s_cbranch_scc1 .Lepi0_full
	s_cmp_eq_u32 s90, 2
	s_cbranch_scc0 .Lepi0_h0
	v_mov_b32_e32 v162, 0x80
	v_lshl_add_u64 v[160:161], v[160:161], 0, v[162:163]
; __device__ __forceinline__ unsigned pk_bf16_rne(float lo, float hi) { f32x2 v = {lo, hi}; bf16x2e b = __builtin_convertvector(v, bf16x2e); return __builtin_bit_cast(unsigned, b); }
; __device__ __forceinline__ float silu_f(float x) { return x * __builtin_amdgcn_rcpf(1.0f + __expf(-x)); }
;     __device__ __forceinline__ void operator()(const f32x4 (&acc)[2][2][4][2], const Unit& u, int wr, int wc, int fr, int fq) const {
; #pragma unroll
;         for (int ai = 0; ai < 2; ++ai)
; #pragma unroll
;             for (int m = 0; m < 4; ++m) {
;                 const int r = u.pm * BM + ai * HALF + wr * 64 + m * 16 + fr;
; #pragma unroll
;                 for (int bj = 0; bj < 2; ++bj) {
;                     const int cb = u.pn * BM + bj * HALF + wc * 32;
;                     const f32x4 v0 = acc[ai][bj][m][0], v1 = acc[ai][bj][m][1];
;                     if (MODE == 0) {
;                         u32x2e w; w.x = pk_bf16_rne(silu_f(v0[0]) * v1[0], silu_f(v0[1]) * v1[1]); w.y = pk_bf16_rne(silu_f(v0[2]) * v1[2], silu_f(v0[3]) * v1[3]);
;                         *(u32x2e*)(Hh + (size_t)r * ldo + (cb >> 1) + 4 * fq) = w;
.Lepi0_h0:
	v_mul_f32_e32 v164, 0xbfb8aa3b, v124
	v_mul_f32_e32 v165, 0xbfb8aa3b, v125
	v_mul_f32_e32 v166, 0xbfb8aa3b, v126
	v_mul_f32_e32 v167, 0xbfb8aa3b, v127
	v_exp_f32_e32 v164, v164
	v_exp_f32_e32 v165, v165
	v_exp_f32_e32 v166, v166
	v_exp_f32_e32 v167, v167
	v_add_f32_e32 v164, 1.0, v164
	v_add_f32_e32 v165, 1.0, v165
	v_add_f32_e32 v166, 1.0, v166
	v_add_f32_e32 v167, 1.0, v167
	v_rcp_f32_e32 v164, v164
	v_rcp_f32_e32 v165, v165
	v_rcp_f32_e32 v166, v166
	v_rcp_f32_e32 v167, v167
	s_nop 0
	v_pk_mul_f32 v[124:125], v[124:125], v[164:165]
	v_pk_mul_f32 v[126:127], v[126:127], v[166:167]
	v_pk_mul_f32 v[124:125], v[120:121], v[124:125]
	v_pk_mul_f32 v[126:127], v[122:123], v[126:127]
	v_cvt_pk_bf16_f32 v176, v124, v125
	v_cvt_pk_bf16_f32 v177, v126, v127
	global_store_dwordx2 v[160:161], v[176:177], off
	s_nop 1
	v_lshl_add_u64 v[160:161], v[160:161], 0, s[4:5]
	v_mul_f32_e32 v164, 0xbfb8aa3b, v108
	v_mul_f32_e32 v165, 0xbfb8aa3b, v109
	v_mul_f32_e32 v166, 0xbfb8aa3b, v110
	v_mul_f32_e32 v167, 0xbfb8aa3b, v111
	v_exp_f32_e32 v164, v164
	v_exp_f32_e32 v165, v165
	v_exp_f32_e32 v166, v166
	v_exp_f32_e32 v167, v167
	v_add_f32_e32 v164, 1.0, v164
	v_add_f32_e32 v165, 1.0, v165
	v_add_f32_e32 v166, 1.0, v166
	v_add_f32_e32 v167, 1.0, v167
	v_rcp_f32_e32 v164, v164
	v_rcp_f32_e32 v165, v165
	v_rcp_f32_e32 v166, v166
	v_rcp_f32_e32 v167, v167
	s_nop 0
	v_pk_mul_f32 v[108:109], v[108:109], v[164:165]
	v_pk_mul_f32 v[110:111], v[110:111], v[166:167]
	v_pk_mul_f32 v[108:109], v[104:105], v[108:109]
	v_pk_mul_f32 v[110:111], v[106:107], v[110:111]
	v_cvt_pk_bf16_f32 v180, v108, v109
	v_cvt_pk_bf16_f32 v181, v110, v111
	global_store_dwordx2 v[160:161], v[180:181], off
	s_nop 1
	v_lshl_add_u64 v[160:161], v[160:161], 0, s[4:5]
	v_mul_f32_e32 v164, 0xbfb8aa3b, v92
	v_mul_f32_e32 v165, 0xbfb8aa3b, v93
	v_mul_f32_e32 v166, 0xbfb8aa3b, v94
	v_mul_f32_e32 v167, 0xbfb8aa3b, v95
	v_exp_f32_e32 v164, v164
	v_exp_f32_e32 v165, v165
	v_exp_f32_e32 v166, v166
	v_exp_f32_e32 v167, v167
	v_add_f32_e32 v164, 1.0, v164
	v_add_f32_e32 v165, 1.0, v165
	v_add_f32_e32 v166, 1.0, v166
	v_add_f32_e32 v167, 1.0, v167
	v_rcp_f32_e32 v164, v164
	v_rcp_f32_e32 v165, v165
	v_rcp_f32_e32 v166, v166
	v_rcp_f32_e32 v167, v167
	s_nop 0
	v_pk_mul_f32 v[92:93], v[92:93], v[164:165]
	v_pk_mul_f32 v[94:95], v[94:95], v[166:167]
	v_pk_mul_f32 v[92:93], v[88:89], v[92:93]
	v_pk_mul_f32 v[94:95], v[90:91], v[94:95]
	v_cvt_pk_bf16_f32 v176, v92, v93
	v_cvt_pk_bf16_f32 v177, v94, v95
	global_store_dwordx2 v[160:161], v[176:177], off
	s_nop 1
	v_lshl_add_u64 v[160:161], v[160:161], 0, s[4:5]
	v_mul_f32_e32 v164, 0xbfb8aa3b, v76
	v_mul_f32_e32 v165, 0xbfb8aa3b, v77
	v_mul_f32_e32 v166, 0xbfb8aa3b, v78
	v_mul_f32_e32 v167, 0xbfb8aa3b, v79
	v_exp_f32_e32 v164, v164
	v_exp_f32_e32 v165, v165
	v_exp_f32_e32 v166, v166
	v_exp_f32_e32 v167, v167
	v_add_f32_e32 v164, 1.0, v164
	v_add_f32_e32 v165, 1.0, v165
	v_add_f32_e32 v166, 1.0, v166
	v_add_f32_e32 v167, 1.0, v167
	v_rcp_f32_e32 v164, v164
	v_rcp_f32_e32 v165, v165
	v_rcp_f32_e32 v166, v166
	v_rcp_f32_e32 v167, v167
	s_nop 0
	v_pk_mul_f32 v[76:77], v[76:77], v[164:165]
	v_pk_mul_f32 v[78:79], v[78:79], v[166:167]
	v_pk_mul_f32 v[76:77], v[72:73], v[76:77]
	v_pk_mul_f32 v[78:79], v[74:75], v[78:79]
	v_cvt_pk_bf16_f32 v180, v76, v77
	v_cvt_pk_bf16_f32 v181, v78, v79
	global_store_dwordx2 v[160:161], v[180:181], off
	s_nop 1
	v_lshl_add_u64 v[160:161], v[160:161], 0, s[28:29]
	v_mul_f32_e32 v164, 0xbfb8aa3b, v60
	v_mul_f32_e32 v165, 0xbfb8aa3b, v61
	v_mul_f32_e32 v166, 0xbfb8aa3b, v62
	v_mul_f32_e32 v167, 0xbfb8aa3b, v63
	v_exp_f32_e32 v164, v164
	v_exp_f32_e32 v165, v165
	v_exp_f32_e32 v166, v166
	v_exp_f32_e32 v167, v167
	v_add_f32_e32 v164, 1.0, v164
	v_add_f32_e32 v165, 1.0, v165
	v_add_f32_e32 v166, 1.0, v166
	v_add_f32_e32 v167, 1.0, v167
	v_rcp_f32_e32 v164, v164
	v_rcp_f32_e32 v165, v165
	v_rcp_f32_e32 v166, v166
	v_rcp_f32_e32 v167, v167
	s_nop 0
	v_pk_mul_f32 v[60:61], v[60:61], v[164:165]
	v_pk_mul_f32 v[62:63], v[62:63], v[166:167]
	v_pk_mul_f32 v[60:61], v[56:57], v[60:61]
	v_pk_mul_f32 v[62:63], v[58:59], v[62:63]
	v_cvt_pk_bf16_f32 v176, v60, v61
	v_cvt_pk_bf16_f32 v177, v62, v63
	global_store_dwordx2 v[160:161], v[176:177], off
	s_nop 1
	v_lshl_add_u64 v[160:161], v[160:161], 0, s[4:5]
	v_mul_f32_e32 v164, 0xbfb8aa3b, v44
	v_mul_f32_e32 v165, 0xbfb8aa3b, v45
	v_mul_f32_e32 v166, 0xbfb8aa3b, v46
	v_mul_f32_e32 v167, 0xbfb8aa3b, v47
	v_exp_f32_e32 v164, v164
	v_exp_f32_e32 v165, v165
	v_exp_f32_e32 v166, v166
	v_exp_f32_e32 v167, v167
	v_add_f32_e32 v164, 1.0, v164
	v_add_f32_e32 v165, 1.0, v165
	v_add_f32_e32 v166, 1.0, v166
	v_add_f32_e32 v167, 1.0, v167
	v_rcp_f32_e32 v164, v164
	v_rcp_f32_e32 v165, v165
	v_rcp_f32_e32 v166, v166
	v_rcp_f32_e32 v167, v167
	s_nop 0
	v_pk_mul_f32 v[44:45], v[44:45], v[164:165]
	v_pk_mul_f32 v[46:47], v[46:47], v[166:167]
	v_pk_mul_f32 v[44:45], v[40:41], v[44:45]
	v_pk_mul_f32 v[46:47], v[42:43], v[46:47]
	v_cvt_pk_bf16_f32 v180, v44, v45
	v_cvt_pk_bf16_f32 v181, v46, v47
	global_store_dwordx2 v[160:161], v[180:181], off
	s_nop 1
	v_lshl_add_u64 v[160:161], v[160:161], 0, s[4:5]
	v_mul_f32_e32 v164, 0xbfb8aa3b, v28
	v_mul_f32_e32 v165, 0xbfb8aa3b, v29
	v_mul_f32_e32 v166, 0xbfb8aa3b, v30
	v_mul_f32_e32 v167, 0xbfb8aa3b, v31
	v_exp_f32_e32 v164, v164
	v_exp_f32_e32 v165, v165
	v_exp_f32_e32 v166, v166
	v_exp_f32_e32 v167, v167
	v_add_f32_e32 v164, 1.0, v164
	v_add_f32_e32 v165, 1.0, v165
	v_add_f32_e32 v166, 1.0, v166
	v_add_f32_e32 v167, 1.0, v167
	v_rcp_f32_e32 v164, v164
	v_rcp_f32_e32 v165, v165
	v_rcp_f32_e32 v166, v166
	v_rcp_f32_e32 v167, v167
	s_nop 0
	v_pk_mul_f32 v[28:29], v[28:29], v[164:165]
	v_pk_mul_f32 v[30:31], v[30:31], v[166:167]
	v_pk_mul_f32 v[28:29], v[24:25], v[28:29]
	v_pk_mul_f32 v[30:31], v[26:27], v[30:31]
	v_cvt_pk_bf16_f32 v176, v28, v29
	v_cvt_pk_bf16_f32 v177, v30, v31
	global_store_dwordx2 v[160:161], v[176:177], off
	s_nop 1
	v_lshl_add_u64 v[160:161], v[160:161], 0, s[4:5]
	v_mul_f32_e32 v164, 0xbfb8aa3b, v12
	v_mul_f32_e32 v165, 0xbfb8aa3b, v13
	v_mul_f32_e32 v166, 0xbfb8aa3b, v14
	v_mul_f32_e32 v167, 0xbfb8aa3b, v15
	v_exp_f32_e32 v164, v164
	v_exp_f32_e32 v165, v165
	v_exp_f32_e32 v166, v166
	v_exp_f32_e32 v167, v167
	v_add_f32_e32 v164, 1.0, v164
	v_add_f32_e32 v165, 1.0, v165
	v_add_f32_e32 v166, 1.0, v166
	v_add_f32_e32 v167, 1.0, v167
	v_rcp_f32_e32 v164, v164
	v_rcp_f32_e32 v165, v165
	v_rcp_f32_e32 v166, v166
	v_rcp_f32_e32 v167, v167
	s_nop 0
	v_pk_mul_f32 v[12:13], v[12:13], v[164:165]
	v_pk_mul_f32 v[14:15], v[14:15], v[166:167]
	v_pk_mul_f32 v[12:13], v[8:9], v[12:13]
	v_pk_mul_f32 v[14:15], v[10:11], v[14:15]
	v_cvt_pk_bf16_f32 v180, v12, v13
	v_cvt_pk_bf16_f32 v181, v14, v15
	global_store_dwordx2 v[160:161], v[180:181], off
	s_branch .LBB0_562
; __device__ __forceinline__ unsigned pk_bf16_rne(float lo, float hi) { f32x2 v = {lo, hi}; bf16x2e b = __builtin_convertvector(v, bf16x2e); return __builtin_bit_cast(unsigned, b); }
; __device__ __forceinline__ float silu_f(float x) { return x * __builtin_amdgcn_rcpf(1.0f + __expf(-x)); }
;     __device__ __forceinline__ void operator()(const f32x4 (&acc)[2][2][4][2], const Unit& u, int wr, int wc, int fr, int fq) const {
; #pragma unroll
;         for (int ai = 0; ai < 2; ++ai)
; #pragma unroll
;             for (int m = 0; m < 4; ++m) {
;                 const int r = u.pm * BM + ai * HALF + wr * 64 + m * 16 + fr;
; #pragma unroll
;                 for (int bj = 0; bj < 2; ++bj) {
;                     const int cb = u.pn * BM + bj * HALF + wc * 32;
;                     const f32x4 v0 = acc[ai][bj][m][0], v1 = acc[ai][bj][m][1];
;                     if (MODE == 0) {
;                         u32x2e w; w.x = pk_bf16_rne(silu_f(v0[0]) * v1[0], silu_f(v0[1]) * v1[1]); w.y = pk_bf16_rne(silu_f(v0[2]) * v1[2], silu_f(v0[3]) * v1[3]);
;                         *(u32x2e*)(Hh + (size_t)r * ldo + (cb >> 1) + 4 * fq) = w;
.Lepi0_full:
	v_mul_f32_e32 v164, 0xbfb8aa3b, v124
	v_mul_f32_e32 v165, 0xbfb8aa3b, v125
	v_mul_f32_e32 v166, 0xbfb8aa3b, v126
	v_mul_f32_e32 v167, 0xbfb8aa3b, v127
	v_mul_f32_e32 v168, 0xbfb8aa3b, v116
	v_mul_f32_e32 v169, 0xbfb8aa3b, v117
	v_mul_f32_e32 v170, 0xbfb8aa3b, v118
	v_mul_f32_e32 v171, 0xbfb8aa3b, v119
	v_exp_f32_e32 v164, v164
	v_exp_f32_e32 v165, v165
	v_exp_f32_e32 v166, v166
	v_exp_f32_e32 v167, v167
	v_exp_f32_e32 v168, v168
	v_exp_f32_e32 v169, v169
	v_exp_f32_e32 v170, v170
	v_exp_f32_e32 v171, v171
	v_add_f32_e32 v164, 1.0, v164
	v_add_f32_e32 v165, 1.0, v165
	v_add_f32_e32 v166, 1.0, v166
	v_add_f32_e32 v167, 1.0, v167
	v_add_f32_e32 v168, 1.0, v168
	v_add_f32_e32 v169, 1.0, v169
	v_add_f32_e32 v170, 1.0, v170
	v_add_f32_e32 v171, 1.0, v171
	v_rcp_f32_e32 v164, v164
	v_rcp_f32_e32 v165, v165
	v_rcp_f32_e32 v166, v166
	v_rcp_f32_e32 v167, v167
	v_rcp_f32_e32 v168, v168
	v_rcp_f32_e32 v169, v169
	v_rcp_f32_e32 v170, v170
	v_rcp_f32_e32 v171, v171
	v_pk_mul_f32 v[124:125], v[124:125], v[164:165]
	v_pk_mul_f32 v[126:127], v[126:127], v[166:167]
	v_pk_mul_f32 v[116:117], v[116:117], v[168:169]
	v_pk_mul_f32 v[118:119], v[118:119], v[170:171]
	v_pk_mul_f32 v[124:125], v[120:121], v[124:125]
	v_pk_mul_f32 v[126:127], v[122:123], v[126:127]
	v_pk_mul_f32 v[116:117], v[112:113], v[116:117]
	v_pk_mul_f32 v[118:119], v[114:115], v[118:119]
	v_cvt_pk_bf16_f32 v176, v124, v125
	v_cvt_pk_bf16_f32 v177, v126, v127
	v_cvt_pk_bf16_f32 v178, v116, v117
	v_cvt_pk_bf16_f32 v179, v118, v119
	global_store_dwordx2 v[160:161], v[176:177], off
	global_store_dwordx2 v[160:161], v[178:179], off offset:128
	s_nop 1
	v_lshl_add_u64 v[160:161], v[160:161], 0, s[4:5]
	v_mul_f32_e32 v164, 0xbfb8aa3b, v108
	v_mul_f32_e32 v165, 0xbfb8aa3b, v109
	v_mul_f32_e32 v166, 0xbfb8aa3b, v110
	v_mul_f32_e32 v167, 0xbfb8aa3b, v111
	v_mul_f32_e32 v168, 0xbfb8aa3b, v100
	v_mul_f32_e32 v169, 0xbfb8aa3b, v101
	v_mul_f32_e32 v170, 0xbfb8aa3b, v102
	v_mul_f32_e32 v171, 0xbfb8aa3b, v103
	v_exp_f32_e32 v164, v164
	v_exp_f32_e32 v165, v165
	v_exp_f32_e32 v166, v166
	v_exp_f32_e32 v167, v167
	v_exp_f32_e32 v168, v168
	v_exp_f32_e32 v169, v169
	v_exp_f32_e32 v170, v170
	v_exp_f32_e32 v171, v171
	v_add_f32_e32 v164, 1.0, v164
	v_add_f32_e32 v165, 1.0, v165
	v_add_f32_e32 v166, 1.0, v166
	v_add_f32_e32 v167, 1.0, v167
	v_add_f32_e32 v168, 1.0, v168
	v_add_f32_e32 v169, 1.0, v169
	v_add_f32_e32 v170, 1.0, v170
	v_add_f32_e32 v171, 1.0, v171
	v_rcp_f32_e32 v164, v164
	v_rcp_f32_e32 v165, v165
	v_rcp_f32_e32 v166, v166
	v_rcp_f32_e32 v167, v167
	v_rcp_f32_e32 v168, v168
	v_rcp_f32_e32 v169, v169
	v_rcp_f32_e32 v170, v170
	v_rcp_f32_e32 v171, v171
	v_pk_mul_f32 v[108:109], v[108:109], v[164:165]
	v_pk_mul_f32 v[110:111], v[110:111], v[166:167]
	v_pk_mul_f32 v[100:101], v[100:101], v[168:169]
	v_pk_mul_f32 v[102:103], v[102:103], v[170:171]
	v_pk_mul_f32 v[108:109], v[104:105], v[108:109]
	v_pk_mul_f32 v[110:111], v[106:107], v[110:111]
	v_pk_mul_f32 v[100:101], v[96:97], v[100:101]
	v_pk_mul_f32 v[102:103], v[98:99], v[102:103]
	v_cvt_pk_bf16_f32 v180, v108, v109
	v_cvt_pk_bf16_f32 v181, v110, v111
	v_cvt_pk_bf16_f32 v182, v100, v101
	v_cvt_pk_bf16_f32 v183, v102, v103
	global_store_dwordx2 v[160:161], v[180:181], off
	global_store_dwordx2 v[160:161], v[182:183], off offset:128
	s_nop 1
	v_lshl_add_u64 v[160:161], v[160:161], 0, s[4:5]
	v_mul_f32_e32 v164, 0xbfb8aa3b, v92
	v_mul_f32_e32 v165, 0xbfb8aa3b, v93
	v_mul_f32_e32 v166, 0xbfb8aa3b, v94
	v_mul_f32_e32 v167, 0xbfb8aa3b, v95
	v_mul_f32_e32 v168, 0xbfb8aa3b, v84
	v_mul_f32_e32 v169, 0xbfb8aa3b, v85
	v_mul_f32_e32 v170, 0xbfb8aa3b, v86
	v_mul_f32_e32 v171, 0xbfb8aa3b, v87
	v_exp_f32_e32 v164, v164
	v_exp_f32_e32 v165, v165
	v_exp_f32_e32 v166, v166
	v_exp_f32_e32 v167, v167
	v_exp_f32_e32 v168, v168
	v_exp_f32_e32 v169, v169
	v_exp_f32_e32 v170, v170
	v_exp_f32_e32 v171, v171
	v_add_f32_e32 v164, 1.0, v164
	v_add_f32_e32 v165, 1.0, v165
	v_add_f32_e32 v166, 1.0, v166
	v_add_f32_e32 v167, 1.0, v167
	v_add_f32_e32 v168, 1.0, v168
	v_add_f32_e32 v169, 1.0, v169
	v_add_f32_e32 v170, 1.0, v170
	v_add_f32_e32 v171, 1.0, v171
	v_rcp_f32_e32 v164, v164
	v_rcp_f32_e32 v165, v165
	v_rcp_f32_e32 v166, v166
	v_rcp_f32_e32 v167, v167
	v_rcp_f32_e32 v168, v168
	v_rcp_f32_e32 v169, v169
	v_rcp_f32_e32 v170, v170
	v_rcp_f32_e32 v171, v171
	v_pk_mul_f32 v[92:93], v[92:93], v[164:165]
	v_pk_mul_f32 v[94:95], v[94:95], v[166:167]
	v_pk_mul_f32 v[84:85], v[84:85], v[168:169]
	v_pk_mul_f32 v[86:87], v[86:87], v[170:171]
	v_pk_mul_f32 v[92:93], v[88:89], v[92:93]
	v_pk_mul_f32 v[94:95], v[90:91], v[94:95]
	v_pk_mul_f32 v[84:85], v[80:81], v[84:85]
	v_pk_mul_f32 v[86:87], v[82:83], v[86:87]
	v_cvt_pk_bf16_f32 v176, v92, v93
	v_cvt_pk_bf16_f32 v177, v94, v95
	v_cvt_pk_bf16_f32 v178, v84, v85
	v_cvt_pk_bf16_f32 v179, v86, v87
	global_store_dwordx2 v[160:161], v[176:177], off
	global_store_dwordx2 v[160:161], v[178:179], off offset:128
	s_nop 1
	v_lshl_add_u64 v[160:161], v[160:161], 0, s[4:5]
	v_mul_f32_e32 v164, 0xbfb8aa3b, v76
	v_mul_f32_e32 v165, 0xbfb8aa3b, v77
	v_mul_f32_e32 v166, 0xbfb8aa3b, v78
	v_mul_f32_e32 v167, 0xbfb8aa3b, v79
	v_mul_f32_e32 v168, 0xbfb8aa3b, v68
	v_mul_f32_e32 v169, 0xbfb8aa3b, v69
	v_mul_f32_e32 v170, 0xbfb8aa3b, v70
	v_mul_f32_e32 v171, 0xbfb8aa3b, v71
	v_exp_f32_e32 v164, v164
	v_exp_f32_e32 v165, v165
	v_exp_f32_e32 v166, v166
	v_exp_f32_e32 v167, v167
	v_exp_f32_e32 v168, v168
	v_exp_f32_e32 v169, v169
	v_exp_f32_e32 v170, v170
	v_exp_f32_e32 v171, v171
	v_add_f32_e32 v164, 1.0, v164
	v_add_f32_e32 v165, 1.0, v165
	v_add_f32_e32 v166, 1.0, v166
	v_add_f32_e32 v167, 1.0, v167
	v_add_f32_e32 v168, 1.0, v168
; __device__ __forceinline__ unsigned pk_bf16_rne(float lo, float hi) { f32x2 v = {lo, hi}; bf16x2e b = __builtin_convertvector(v, bf16x2e); return __builtin_bit_cast(unsigned, b); }
; __device__ __forceinline__ float silu_f(float x) { return x * __builtin_amdgcn_rcpf(1.0f + __expf(-x)); }
;     __device__ __forceinline__ void operator()(const f32x4 (&acc)[2][2][4][2], const Unit& u, int wr, int wc, int fr, int fq) const {
; #pragma unroll
;         for (int ai = 0; ai < 2; ++ai)
; #pragma unroll
;             for (int m = 0; m < 4; ++m) {
;                 const int r = u.pm * BM + ai * HALF + wr * 64 + m * 16 + fr;
; #pragma unroll
;                 for (int bj = 0; bj < 2; ++bj) {
;                     const int cb = u.pn * BM + bj * HALF + wc * 32;
;                     const f32x4 v0 = acc[ai][bj][m][0], v1 = acc[ai][bj][m][1];
;                     if (MODE == 0) {
;                         u32x2e w; w.x = pk_bf16_rne(silu_f(v0[0]) * v1[0], silu_f(v0[1]) * v1[1]); w.y = pk_bf16_rne(silu_f(v0[2]) * v1[2], silu_f(v0[3]) * v1[3]);
;                         *(u32x2e*)(Hh + (size_t)r * ldo + (cb >> 1) + 4 * fq) = w;
	v_add_f32_e32 v169, 1.0, v169
	v_add_f32_e32 v170, 1.0, v170
	v_add_f32_e32 v171, 1.0, v171
	v_rcp_f32_e32 v164, v164
	v_rcp_f32_e32 v165, v165
	v_rcp_f32_e32 v166, v166
	v_rcp_f32_e32 v167, v167
	v_rcp_f32_e32 v168, v168
	v_rcp_f32_e32 v169, v169
	v_rcp_f32_e32 v170, v170
	v_rcp_f32_e32 v171, v171
	v_pk_mul_f32 v[76:77], v[76:77], v[164:165]
	v_pk_mul_f32 v[78:79], v[78:79], v[166:167]
	v_pk_mul_f32 v[68:69], v[68:69], v[168:169]
	v_pk_mul_f32 v[70:71], v[70:71], v[170:171]
	v_pk_mul_f32 v[76:77], v[72:73], v[76:77]
	v_pk_mul_f32 v[78:79], v[74:75], v[78:79]
	v_pk_mul_f32 v[68:69], v[64:65], v[68:69]
	v_pk_mul_f32 v[70:71], v[66:67], v[70:71]
	v_cvt_pk_bf16_f32 v180, v76, v77
	v_cvt_pk_bf16_f32 v181, v78, v79
	v_cvt_pk_bf16_f32 v182, v68, v69
	v_cvt_pk_bf16_f32 v183, v70, v71
	global_store_dwordx2 v[160:161], v[180:181], off
	global_store_dwordx2 v[160:161], v[182:183], off offset:128
	s_nop 1
	v_lshl_add_u64 v[160:161], v[160:161], 0, s[28:29]
	v_mul_f32_e32 v164, 0xbfb8aa3b, v60
	v_mul_f32_e32 v165, 0xbfb8aa3b, v61
	v_mul_f32_e32 v166, 0xbfb8aa3b, v62
	v_mul_f32_e32 v167, 0xbfb8aa3b, v63
	v_mul_f32_e32 v168, 0xbfb8aa3b, v52
	v_mul_f32_e32 v169, 0xbfb8aa3b, v53
	v_mul_f32_e32 v170, 0xbfb8aa3b, v54
	v_mul_f32_e32 v171, 0xbfb8aa3b, v55
	v_exp_f32_e32 v164, v164
	v_exp_f32_e32 v165, v165
	v_exp_f32_e32 v166, v166
	v_exp_f32_e32 v167, v167
	v_exp_f32_e32 v168, v168
	v_exp_f32_e32 v169, v169
	v_exp_f32_e32 v170, v170
	v_exp_f32_e32 v171, v171
	v_add_f32_e32 v164, 1.0, v164
	v_add_f32_e32 v165, 1.0, v165
	v_add_f32_e32 v166, 1.0, v166
	v_add_f32_e32 v167, 1.0, v167
	v_add_f32_e32 v168, 1.0, v168
	v_add_f32_e32 v169, 1.0, v169
	v_add_f32_e32 v170, 1.0, v170
	v_add_f32_e32 v171, 1.0, v171
	v_rcp_f32_e32 v164, v164
	v_rcp_f32_e32 v165, v165
	v_rcp_f32_e32 v166, v166
	v_rcp_f32_e32 v167, v167
	v_rcp_f32_e32 v168, v168
	v_rcp_f32_e32 v169, v169
	v_rcp_f32_e32 v170, v170
	v_rcp_f32_e32 v171, v171
	v_pk_mul_f32 v[60:61], v[60:61], v[164:165]
	v_pk_mul_f32 v[62:63], v[62:63], v[166:167]
	v_pk_mul_f32 v[52:53], v[52:53], v[168:169]
	v_pk_mul_f32 v[54:55], v[54:55], v[170:171]
	v_pk_mul_f32 v[60:61], v[56:57], v[60:61]
	v_pk_mul_f32 v[62:63], v[58:59], v[62:63]
	v_pk_mul_f32 v[52:53], v[48:49], v[52:53]
	v_pk_mul_f32 v[54:55], v[50:51], v[54:55]
	v_cvt_pk_bf16_f32 v176, v60, v61
	v_cvt_pk_bf16_f32 v177, v62, v63
	v_cvt_pk_bf16_f32 v178, v52, v53
	v_cvt_pk_bf16_f32 v179, v54, v55
	global_store_dwordx2 v[160:161], v[176:177], off
	global_store_dwordx2 v[160:161], v[178:179], off offset:128
	s_nop 1
	v_lshl_add_u64 v[160:161], v[160:161], 0, s[4:5]
	v_mul_f32_e32 v164, 0xbfb8aa3b, v44
	v_mul_f32_e32 v165, 0xbfb8aa3b, v45
	v_mul_f32_e32 v166, 0xbfb8aa3b, v46
	v_mul_f32_e32 v167, 0xbfb8aa3b, v47
	v_mul_f32_e32 v168, 0xbfb8aa3b, v36
	v_mul_f32_e32 v169, 0xbfb8aa3b, v37
	v_mul_f32_e32 v170, 0xbfb8aa3b, v38
	v_mul_f32_e32 v171, 0xbfb8aa3b, v39
	v_exp_f32_e32 v164, v164
	v_exp_f32_e32 v165, v165
	v_exp_f32_e32 v166, v166
	v_exp_f32_e32 v167, v167
	v_exp_f32_e32 v168, v168
	v_exp_f32_e32 v169, v169
	v_exp_f32_e32 v170, v170
	v_exp_f32_e32 v171, v171
	v_add_f32_e32 v164, 1.0, v164
	v_add_f32_e32 v165, 1.0, v165
	v_add_f32_e32 v166, 1.0, v166
	v_add_f32_e32 v167, 1.0, v167
	v_add_f32_e32 v168, 1.0, v168
	v_add_f32_e32 v169, 1.0, v169
	v_add_f32_e32 v170, 1.0, v170
	v_add_f32_e32 v171, 1.0, v171
	v_rcp_f32_e32 v164, v164
	v_rcp_f32_e32 v165, v165
	v_rcp_f32_e32 v166, v166
	v_rcp_f32_e32 v167, v167
	v_rcp_f32_e32 v168, v168
	v_rcp_f32_e32 v169, v169
	v_rcp_f32_e32 v170, v170
	v_rcp_f32_e32 v171, v171
	v_pk_mul_f32 v[44:45], v[44:45], v[164:165]
	v_pk_mul_f32 v[46:47], v[46:47], v[166:167]
	v_pk_mul_f32 v[36:37], v[36:37], v[168:169]
; __device__ __forceinline__ unsigned pk_bf16_rne(float lo, float hi) { f32x2 v = {lo, hi}; bf16x2e b = __builtin_convertvector(v, bf16x2e); return __builtin_bit_cast(unsigned, b); }
; __device__ __forceinline__ float silu_f(float x) { return x * __builtin_amdgcn_rcpf(1.0f + __expf(-x)); }
;     __device__ __forceinline__ void operator()(const f32x4 (&acc)[2][2][4][2], const Unit& u, int wr, int wc, int fr, int fq) const {
; #pragma unroll
;         for (int ai = 0; ai < 2; ++ai)
; #pragma unroll
;             for (int m = 0; m < 4; ++m) {
;                 const int r = u.pm * BM + ai * HALF + wr * 64 + m * 16 + fr;
; #pragma unroll
;                 for (int bj = 0; bj < 2; ++bj) {
;                     const int cb = u.pn * BM + bj * HALF + wc * 32;
;                     const f32x4 v0 = acc[ai][bj][m][0], v1 = acc[ai][bj][m][1];
;                     if (MODE == 0) {
;                         u32x2e w; w.x = pk_bf16_rne(silu_f(v0[0]) * v1[0], silu_f(v0[1]) * v1[1]); w.y = pk_bf16_rne(silu_f(v0[2]) * v1[2], silu_f(v0[3]) * v1[3]);
;                         *(u32x2e*)(Hh + (size_t)r * ldo + (cb >> 1) + 4 * fq) = w;
	v_pk_mul_f32 v[38:39], v[38:39], v[170:171]
	v_pk_mul_f32 v[44:45], v[40:41], v[44:45]
	v_pk_mul_f32 v[46:47], v[42:43], v[46:47]
	v_pk_mul_f32 v[36:37], v[32:33], v[36:37]
	v_pk_mul_f32 v[38:39], v[34:35], v[38:39]
	v_cvt_pk_bf16_f32 v180, v44, v45
	v_cvt_pk_bf16_f32 v181, v46, v47
	v_cvt_pk_bf16_f32 v182, v36, v37
	v_cvt_pk_bf16_f32 v183, v38, v39
	global_store_dwordx2 v[160:161], v[180:181], off
	global_store_dwordx2 v[160:161], v[182:183], off offset:128
	s_nop 1
	v_lshl_add_u64 v[160:161], v[160:161], 0, s[4:5]
	v_mul_f32_e32 v164, 0xbfb8aa3b, v28
	v_mul_f32_e32 v165, 0xbfb8aa3b, v29
	v_mul_f32_e32 v166, 0xbfb8aa3b, v30
	v_mul_f32_e32 v167, 0xbfb8aa3b, v31
	v_mul_f32_e32 v168, 0xbfb8aa3b, v20
	v_mul_f32_e32 v169, 0xbfb8aa3b, v21
	v_mul_f32_e32 v170, 0xbfb8aa3b, v22
	v_mul_f32_e32 v171, 0xbfb8aa3b, v23
	v_exp_f32_e32 v164, v164
	v_exp_f32_e32 v165, v165
	v_exp_f32_e32 v166, v166
	v_exp_f32_e32 v167, v167
	v_exp_f32_e32 v168, v168
	v_exp_f32_e32 v169, v169
	v_exp_f32_e32 v170, v170
	v_exp_f32_e32 v171, v171
	v_add_f32_e32 v164, 1.0, v164
	v_add_f32_e32 v165, 1.0, v165
	v_add_f32_e32 v166, 1.0, v166
	v_add_f32_e32 v167, 1.0, v167
	v_add_f32_e32 v168, 1.0, v168
	v_add_f32_e32 v169, 1.0, v169
	v_add_f32_e32 v170, 1.0, v170
	v_add_f32_e32 v171, 1.0, v171
	v_rcp_f32_e32 v164, v164
	v_rcp_f32_e32 v165, v165
	v_rcp_f32_e32 v166, v166
	v_rcp_f32_e32 v167, v167
	v_rcp_f32_e32 v168, v168
	v_rcp_f32_e32 v169, v169
	v_rcp_f32_e32 v170, v170
	v_rcp_f32_e32 v171, v171
	v_pk_mul_f32 v[28:29], v[28:29], v[164:165]
	v_pk_mul_f32 v[30:31], v[30:31], v[166:167]
	v_pk_mul_f32 v[20:21], v[20:21], v[168:169]
	v_pk_mul_f32 v[22:23], v[22:23], v[170:171]
	v_pk_mul_f32 v[28:29], v[24:25], v[28:29]
	v_pk_mul_f32 v[30:31], v[26:27], v[30:31]
	v_pk_mul_f32 v[20:21], v[16:17], v[20:21]
	v_pk_mul_f32 v[22:23], v[18:19], v[22:23]
	v_cvt_pk_bf16_f32 v176, v28, v29
	v_cvt_pk_bf16_f32 v177, v30, v31
	v_cvt_pk_bf16_f32 v178, v20, v21
	v_cvt_pk_bf16_f32 v179, v22, v23
	global_store_dwordx2 v[160:161], v[176:177], off
	global_store_dwordx2 v[160:161], v[178:179], off offset:128
	s_nop 1
	v_lshl_add_u64 v[160:161], v[160:161], 0, s[4:5]
	v_mul_f32_e32 v164, 0xbfb8aa3b, v12
	v_mul_f32_e32 v165, 0xbfb8aa3b, v13
	v_mul_f32_e32 v166, 0xbfb8aa3b, v14
	v_mul_f32_e32 v167, 0xbfb8aa3b, v15
	v_mul_f32_e32 v168, 0xbfb8aa3b, v4
	v_mul_f32_e32 v169, 0xbfb8aa3b, v5
	v_mul_f32_e32 v170, 0xbfb8aa3b, v6
	v_mul_f32_e32 v171, 0xbfb8aa3b, v7
	v_exp_f32_e32 v164, v164
	v_exp_f32_e32 v165, v165
	v_exp_f32_e32 v166, v166
	v_exp_f32_e32 v167, v167
	v_exp_f32_e32 v168, v168
	v_exp_f32_e32 v169, v169
	v_exp_f32_e32 v170, v170
	v_exp_f32_e32 v171, v171
	v_add_f32_e32 v164, 1.0, v164
	v_add_f32_e32 v165, 1.0, v165
	v_add_f32_e32 v166, 1.0, v166
	v_add_f32_e32 v167, 1.0, v167
	v_add_f32_e32 v168, 1.0, v168
	v_add_f32_e32 v169, 1.0, v169
	v_add_f32_e32 v170, 1.0, v170
	v_add_f32_e32 v171, 1.0, v171
	v_rcp_f32_e32 v164, v164
	v_rcp_f32_e32 v165, v165
	v_rcp_f32_e32 v166, v166
	v_rcp_f32_e32 v167, v167
	v_rcp_f32_e32 v168, v168
	v_rcp_f32_e32 v169, v169
	v_rcp_f32_e32 v170, v170
	v_rcp_f32_e32 v171, v171
	v_pk_mul_f32 v[12:13], v[12:13], v[164:165]
	v_pk_mul_f32 v[14:15], v[14:15], v[166:167]
	v_pk_mul_f32 v[4:5], v[4:5], v[168:169]
	v_pk_mul_f32 v[6:7], v[6:7], v[170:171]
	v_pk_mul_f32 v[12:13], v[8:9], v[12:13]
	v_pk_mul_f32 v[14:15], v[10:11], v[14:15]
	v_pk_mul_f32 v[4:5], v[0:1], v[4:5]
	v_pk_mul_f32 v[6:7], v[2:3], v[6:7]
	v_cvt_pk_bf16_f32 v180, v12, v13
	v_cvt_pk_bf16_f32 v181, v14, v15
	v_cvt_pk_bf16_f32 v182, v4, v5
	v_cvt_pk_bf16_f32 v183, v6, v7
	global_store_dwordx2 v[160:161], v[180:181], off
	global_store_dwordx2 v[160:161], v[182:183], off offset:128
	s_branch .LBB0_562
